# SSD prompt: wave-0 dt*A prefix sum via DPP scan instead of 6 dependent ds_bpermute round trips
# baseline (speedup 1.0000x reference)
.LBB0_846:
	s_and_saveexec_b64 s[78:79], s[4:5]
	s_cbranch_execz .LBB0_848
	s_waitcnt vmcnt(1)
	v_mul_f32_e64 v42, v95, -v184
	s_nop 1
	v_add_f32_dpp v42, v42, v42 row_shr:1 row_mask:0xf bank_mask:0xf
	s_nop 1
	v_add_f32_dpp v42, v42, v42 row_shr:2 row_mask:0xf bank_mask:0xf
	s_nop 1
	v_add_f32_dpp v42, v42, v42 row_shr:4 row_mask:0xf bank_mask:0xf
	s_nop 1
	v_add_f32_dpp v42, v42, v42 row_shr:8 row_mask:0xf bank_mask:0xf
	s_nop 1
	v_add_f32_dpp v42, v42, v42 row_bcast:15 row_mask:0xa bank_mask:0xf
	s_nop 1
	v_add_f32_dpp v42, v42, v42 row_bcast:31 row_mask:0xc bank_mask:0xf
	ds_write_b32 v65, v42
	ds_write_b32 v85, v95
